# attention phase start: lam dot-product butterflies via DPP + permlane16/32 swaps instead of 12 ds_bpermute hops (on v30)
# speedup vs baseline: 1.0036x; 1.0036x over previous
.LBB0_471:
	s_or_b64 exec, exec, s[8:9]
	s_mov_b64 s[8:9], s[0:1]
	s_waitcnt lgkmcnt(0)
	v_mov_b32_e32 v0, v224
	s_barrier
	s_load_dwordx8 s[12:19], s[8:9], 0x18
	v_lshlrev_b32_e32 v0, 2, v0
	v_and_b32_e32 v1, 0xfc, v0
	s_waitcnt lgkmcnt(0)
	global_load_dword v2, v1, s[12:13]
	global_load_dword v3, v1, s[14:15]
	global_load_dword v4, v1, s[16:17]
	global_load_dword v5, v1, s[18:19]
	v_bfrev_b32_e32 v1, 0.5
	v_bitop3_b32 v6, v0, 4, v1 bitop3:0x6c
	s_movk_i32 s11, 0x80
	s_mov_b32 s10, 0x3fb8aa3b
	s_mov_b32 s12, 0xc2ce8ed0
	s_bfe_u32 s79, s77, 0x20005
	s_mov_b32 s13, 0x42b17218
	s_not_b32 s14, s79
	s_and_b32 s78, s77, 15
	s_waitcnt vmcnt(2)
	v_mul_f32_e32 v7, v2, v3
	s_nop 1
	v_mov_b32_dpp v7, v7 quad_perm:[1,0,3,2] row_mask:0xf bank_mask:0xf
	s_waitcnt vmcnt(0)
	v_mul_f32_e32 v8, v4, v5
	s_nop 1
	v_mov_b32_dpp v6, v8 quad_perm:[1,0,3,2] row_mask:0xf bank_mask:0xf
	v_bitop3_b32 v8, v0, 8, v1 bitop3:0x6c
	s_waitcnt lgkmcnt(1)
	v_fmac_f32_e32 v7, v2, v3
	s_nop 1
	v_mov_b32_dpp v2, v7 quad_perm:[2,3,0,1] row_mask:0xf bank_mask:0xf
	s_waitcnt lgkmcnt(1)
	v_fmac_f32_e32 v6, v4, v5
	s_nop 1
	v_mov_b32_dpp v3, v6 quad_perm:[2,3,0,1] row_mask:0xf bank_mask:0xf
	v_bitop3_b32 v4, v0, 16, v1 bitop3:0x6c
	s_waitcnt lgkmcnt(1)
	v_add_f32_e32 v2, v7, v2
	s_nop 1
	v_mov_b32_dpp v5, v2 row_half_mirror row_mask:0xf bank_mask:0xf
	s_waitcnt lgkmcnt(1)
	v_add_f32_e32 v3, v6, v3
	s_nop 1
	v_mov_b32_dpp v4, v3 row_half_mirror row_mask:0xf bank_mask:0xf
	v_bitop3_b32 v6, v0, 32, v1 bitop3:0x6c
	s_waitcnt lgkmcnt(1)
	v_add_f32_e32 v2, v2, v5
	s_waitcnt lgkmcnt(0)
	v_add_f32_e32 v3, v3, v4
	s_nop 1
	v_mov_b32_dpp v4, v2 row_mirror row_mask:0xf bank_mask:0xf
	s_nop 1
	v_mov_b32_dpp v5, v3 row_mirror row_mask:0xf bank_mask:0xf
	v_bitop3_b32 v6, v0, 64, v1 bitop3:0x6c
	v_bitop3_b32 v0, v0, s11, v1 bitop3:0x6c
	s_lshl_b32 s11, s14, 1
	s_waitcnt lgkmcnt(1)
	v_add_f32_e32 v2, v2, v4
	s_waitcnt lgkmcnt(0)
	v_add_f32_e32 v3, v3, v5
	v_mov_b32_e32 v4, v2
	s_nop 1
	v_permlane16_swap_b32_e32 v2, v4
	v_mov_b32_e32 v5, v3
	s_nop 1
	v_permlane16_swap_b32_e32 v3, v5
	v_mov_b32_e32 v6, 0x7f800000
	s_cmpk_lt_i32 s77, 0x100
	s_waitcnt lgkmcnt(1)
	v_add_f32_e32 v1, v2, v4
	s_waitcnt lgkmcnt(0)
	v_add_f32_e32 v2, v3, v5
	v_mov_b32_e32 v3, v1
	s_nop 1
	v_permlane32_swap_b32_e32 v1, v3
	v_mov_b32_e32 v0, v2
	s_nop 1
	v_permlane32_swap_b32_e32 v2, v0
	v_ldexp_f32 v4, 1.0, s11
	v_mul_f32_e32 v225, 0x3fb8aa3b, v4
	s_waitcnt lgkmcnt(1)
	v_add_f32_e32 v1, v1, v3
	s_waitcnt lgkmcnt(0)
	v_add_f32_e32 v0, v2, v0
	v_mul_f32_e32 v2, 0x3fb8aa3b, v1
	v_mul_f32_e32 v3, 0x3fb8aa3b, v0
	v_fma_f32 v5, v1, s10, -v2
	v_rndne_f32_e32 v7, v2
	v_fma_f32 v8, v0, s10, -v3
	v_rndne_f32_e32 v9, v3
	v_fmac_f32_e32 v5, 0x32a5705f, v1
	v_sub_f32_e32 v2, v2, v7
	v_fmac_f32_e32 v8, 0x32a5705f, v0
	v_sub_f32_e32 v3, v3, v9
	v_add_f32_e32 v2, v2, v5
	v_cvt_i32_f32_e32 v7, v7
	v_add_f32_e32 v3, v3, v8
	v_exp_f32_e32 v2, v2
	v_cvt_i32_f32_e32 v9, v9
	v_exp_f32_e32 v3, v3
	v_cmp_ngt_f32_e32 vcc, s12, v1
	v_ldexp_f32 v2, v2, v7
	s_cselect_b64 s[10:11], -1, 0
	v_ldexp_f32 v3, v3, v9
	v_cndmask_b32_e32 v2, 0, v2, vcc
	v_cmp_ngt_f32_e32 vcc, s12, v0
	v_writelane_b32 v252, s10, 3
	s_cmpk_gt_i32 s77, 0xff
	v_cndmask_b32_e32 v3, 0, v3, vcc
	v_cmp_nlt_f32_e32 vcc, s13, v1
	v_writelane_b32 v252, s11, 4
	s_nop 0
	v_cndmask_b32_e32 v1, v6, v2, vcc
	v_cmp_nlt_f32_e32 vcc, s13, v0
	s_nop 1
	v_cndmask_b32_e32 v0, v6, v3, vcc
	v_sub_f32_e32 v0, v1, v0
	s_nop 0
	v_readfirstlane_b32 s10, v0
	s_cbranch_scc1 .LBB0_574
	s_load_dwordx2 s[12:13], s[8:9], 0xa0
	s_load_dwordx2 s[16:17], s[8:9], 0x38
	s_lshl_b32 s14, s77, 4
	s_lshl_b32 s11, s79, 9
	s_and_b32 s14, s14, 0xfffff800
	s_or_b32 s14, s11, s14
	s_ashr_i32 s15, s14, 31
	s_lshl_b64 s[14:15], s[14:15], 2
	s_waitcnt lgkmcnt(0)
	s_add_u32 s8, s12, s14
	s_addc_u32 s9, s13, s15
	v_mov_b32_e32 v0, 0x3e4ccccc
	s_add_u32 s53, s8, 0xe009000
	v_add_f32_e32 v212, s10, v0
	v_readlane_b32 s10, v252, 0
	s_addc_u32 s66, s9, 0
	s_ashr_i32 s8, s77, 7
	s_xor_b32 s67, s78, 31
	s_lshl_b32 s9, s79, 8
	s_and_b32 s10, s10, 0x80
	s_add_u32 s11, s12, s9
	s_addc_u32 s12, s13, 0
	s_add_u32 s10, s11, s10
	s_addc_u32 s13, s12, 0
	s_add_u32 s68, s10, 0x5000000
	s_addc_u32 s69, s13, 0
	s_add_u32 s80, s11, 0xc000000
	s_addc_u32 s81, s12, 0
	s_add_u32 s82, s11, 0xa000000
	s_addc_u32 s83, s12, 0
	s_ashr_i32 s9, s8, 31
	s_lshl_b64 s[18:19], s[8:9], 13
	s_mul_hi_i32 s9, s8, 0x2800000
	s_mul_i32 s8, s8, 0x2800000
	s_add_u32 s10, s10, s8
	s_addc_u32 s13, s13, s9
	s_add_u32 s34, s10, 0x5000400
	s_addc_u32 s35, s13, 0
	s_add_u32 s8, s11, s8
	s_addc_u32 s9, s12, s9
	s_add_u32 s36, s8, 0x5000800
	s_addc_u32 s37, s9, 0
	s_bitcmp1_b32 s77, 4
	s_cselect_b64 s[38:39], -1, 0
	v_mov_b32_e32 v213, v212
	s_mov_b64 s[10:11], -1
	s_movk_i32 s84, 0x7fff
	s_mov_b32 s85, 0xffff0000
	v_mov_b32_e32 v1, 0
	s_mov_b64 s[40:41], 0x50000
	s_movk_i32 s86, 0x2000
	s_mov_b64 s[42:43], 0xa0000
	s_movk_i32 s87, 0x4000
	s_mov_b64 s[44:45], 0xf0000
	s_mov_b64 s[46:47], 0x50080
	s_mov_b64 s[48:49], 0x140000
	s_mov_b32 s88, 0x41000000
	s_mov_b64 s[50:51], 0x190000
	s_mov_b32 s15, 0x20000
	s_brev_b32 s14, -2
	v_mov_b32_e32 v226, 1
	s_mov_b32 s52, 0x3f4ccccd
	v_mov_b32_e32 v227, 0x3727c5ac
	v_mov_b32_e32 v228, 0xff800000
	v_mov_b32_e32 v229, 0x4040
	s_branch .LBB0_476

.LBB0_1341:
	s_or_b64 exec, exec, s[10:11]
	s_mov_b64 s[10:11], s[0:1]
	s_waitcnt lgkmcnt(0)
	v_mov_b32_e32 v0, v224
	s_barrier
	s_load_dwordx8 s[12:19], s[10:11], 0x18
	v_lshlrev_b32_e32 v0, 2, v0
	v_and_b32_e32 v1, 0xfc, v0
	s_waitcnt lgkmcnt(0)
	global_load_dword v2, v1, s[12:13] offset:256
	global_load_dword v3, v1, s[14:15] offset:256
	global_load_dword v4, v1, s[16:17] offset:256
	global_load_dword v5, v1, s[18:19] offset:256
	v_bfrev_b32_e32 v1, 0.5
	v_bitop3_b32 v6, v0, 4, v1 bitop3:0x6c
	s_movk_i32 s12, 0x80
	s_mov_b32 s13, 0x3fb8aa3b
	s_mov_b32 s14, 0x42b17218
	s_waitcnt vmcnt(2)
	v_mul_f32_e32 v7, v2, v3
	s_nop 1
	v_mov_b32_dpp v7, v7 quad_perm:[1,0,3,2] row_mask:0xf bank_mask:0xf
	s_waitcnt vmcnt(0)
	v_mul_f32_e32 v8, v4, v5
	s_nop 1
	v_mov_b32_dpp v6, v8 quad_perm:[1,0,3,2] row_mask:0xf bank_mask:0xf
	v_bitop3_b32 v8, v0, 8, v1 bitop3:0x6c
	s_waitcnt lgkmcnt(1)
	v_fmac_f32_e32 v7, v2, v3
	s_nop 1
	v_mov_b32_dpp v2, v7 quad_perm:[2,3,0,1] row_mask:0xf bank_mask:0xf
	s_waitcnt lgkmcnt(1)
	v_fmac_f32_e32 v6, v4, v5
	s_nop 1
	v_mov_b32_dpp v3, v6 quad_perm:[2,3,0,1] row_mask:0xf bank_mask:0xf
	v_bitop3_b32 v4, v0, 16, v1 bitop3:0x6c
	s_waitcnt lgkmcnt(1)
	v_add_f32_e32 v2, v7, v2
	s_nop 1
	v_mov_b32_dpp v5, v2 row_half_mirror row_mask:0xf bank_mask:0xf
	s_waitcnt lgkmcnt(1)
	v_add_f32_e32 v3, v6, v3
	s_nop 1
	v_mov_b32_dpp v4, v3 row_half_mirror row_mask:0xf bank_mask:0xf
	v_bitop3_b32 v6, v0, 32, v1 bitop3:0x6c
	s_waitcnt lgkmcnt(1)
	v_add_f32_e32 v2, v2, v5
	s_waitcnt lgkmcnt(0)
	v_add_f32_e32 v3, v3, v4
	s_nop 1
	v_mov_b32_dpp v4, v2 row_mirror row_mask:0xf bank_mask:0xf
	s_nop 1
	v_mov_b32_dpp v5, v3 row_mirror row_mask:0xf bank_mask:0xf
	v_bitop3_b32 v6, v0, 64, v1 bitop3:0x6c
	v_bitop3_b32 v0, v0, s12, v1 bitop3:0x6c
	s_mov_b32 s12, 0xc2ce8ed0
	s_waitcnt lgkmcnt(1)
	v_add_f32_e32 v2, v2, v4
	s_waitcnt lgkmcnt(0)
	v_add_f32_e32 v3, v3, v5
	v_mov_b32_e32 v4, v2
	s_nop 1
	v_permlane16_swap_b32_e32 v2, v4
	v_mov_b32_e32 v5, v3
	s_nop 1
	v_permlane16_swap_b32_e32 v3, v5
	s_waitcnt lgkmcnt(1)
	v_add_f32_e32 v1, v2, v4
	s_waitcnt lgkmcnt(0)
	v_add_f32_e32 v2, v3, v5
	v_mov_b32_e32 v3, v1
	s_nop 1
	v_permlane32_swap_b32_e32 v1, v3
	v_mov_b32_e32 v0, v2
	s_nop 1
	v_permlane32_swap_b32_e32 v2, v0
	v_mov_b32_e32 v4, 0x7f800000
	s_waitcnt lgkmcnt(1)
	v_add_f32_e32 v1, v1, v3
	s_waitcnt lgkmcnt(0)
	v_add_f32_e32 v0, v2, v0
	v_mul_f32_e32 v2, 0x3fb8aa3b, v1
	v_mul_f32_e32 v3, 0x3fb8aa3b, v0
	v_fma_f32 v5, v1, s13, -v2
	v_rndne_f32_e32 v6, v2
	v_fma_f32 v7, v0, s13, -v3
	v_rndne_f32_e32 v8, v3
	v_fmac_f32_e32 v5, 0x32a5705f, v1
	v_sub_f32_e32 v2, v2, v6
	v_fmac_f32_e32 v7, 0x32a5705f, v0
	v_sub_f32_e32 v3, v3, v8
	v_add_f32_e32 v2, v2, v5
	v_cvt_i32_f32_e32 v6, v6
	v_add_f32_e32 v3, v3, v7
	v_exp_f32_e32 v2, v2
	v_cvt_i32_f32_e32 v8, v8
	v_exp_f32_e32 v3, v3
	v_cmp_ngt_f32_e32 vcc, s12, v1
	v_ldexp_f32 v2, v2, v6
	v_ldexp_f32 v3, v3, v8
	v_cndmask_b32_e32 v2, 0, v2, vcc
	v_cmp_ngt_f32_e32 vcc, s12, v0
	v_readlane_b32 s12, v252, 3
	v_readlane_b32 s13, v252, 4
	v_cndmask_b32_e32 v3, 0, v3, vcc
	v_cmp_nlt_f32_e32 vcc, s14, v1
	s_nop 1
	v_cndmask_b32_e32 v1, v4, v2, vcc
	v_cmp_nlt_f32_e32 vcc, s14, v0
	s_nop 1
	v_cndmask_b32_e32 v0, v4, v3, vcc
	v_sub_f32_e32 v0, v1, v0
	s_andn2_b64 vcc, exec, s[12:13]
	v_readfirstlane_b32 s12, v0
	s_cbranch_vccnz .LBB0_1444
	s_ashr_i32 s20, s77, 7
	s_load_dwordx2 s[14:15], s[10:11], 0xa0
	s_lshl_b32 s13, s79, 9
	s_lshl_b32 s16, s20, 11
	s_or_b32 s13, s16, s13
	s_add_i32 s16, s13, 0x1000
	s_ashr_i32 s17, s16, 31
	s_lshl_b64 s[18:19], s[16:17], 2
	s_load_dwordx2 s[16:17], s[10:11], 0x38
	s_waitcnt lgkmcnt(0)
	s_add_u32 s10, s14, s18
	s_addc_u32 s11, s15, s19
	s_add_u32 s51, s10, 0xe009000
	s_addc_u32 s66, s11, 0
	v_readlane_b32 s11, v252, 0
	s_xor_b32 s67, s78, 31
	s_lshl_b32 s10, s79, 8
	s_and_b32 s11, s11, 0x80
	v_mov_b32_e32 v0, 0x3eb60549
	s_add_u32 s10, s14, s10
	v_add_f32_e32 v212, s12, v0
	s_addc_u32 s12, s15, 0
	s_add_u32 s11, s10, s11
	s_addc_u32 s13, s12, 0
	s_add_u32 s68, s11, 0x5000000
	s_addc_u32 s69, s13, 0
	s_add_u32 s79, s10, 0xc000000
	s_addc_u32 s82, s12, 0
	s_add_u32 s83, s10, 0xa000000
	s_addc_u32 s84, s12, 0
	s_ashr_i32 s21, s20, 31
	s_lshl_b64 s[18:19], s[20:21], 13
	s_mul_i32 s15, s20, 0x2800000
	s_mul_hi_i32 s14, s20, 0x2800000
	s_add_u32 s11, s11, s15
	s_addc_u32 s13, s13, s14
	s_add_u32 s20, s11, 0x5000400
	s_addc_u32 s21, s13, 0
	s_add_u32 s10, s10, s15
	s_addc_u32 s11, s12, s14
	s_add_u32 s22, s10, 0x5000800
	s_addc_u32 s23, s11, 0
	s_bitcmp1_b32 s77, 4
	s_cselect_b64 s[36:37], -1, 0
	v_mov_b32_e32 v213, v212
	s_mov_b64 s[12:13], -1
	s_movk_i32 s85, 0x7fff
	s_mov_b32 s86, 0xffff0000
	v_mov_b32_e32 v1, 0
	s_mov_b64 s[38:39], 0x50000
	s_mov_b64 s[40:41], 0xa0000
	s_mov_b64 s[42:43], 0xf0000
	s_mov_b64 s[44:45], 0x50080
	s_mov_b64 s[46:47], 0x140000
	s_mov_b32 s87, 0x41000000
	s_mov_b64 s[48:49], 0x190000
	s_mov_b32 s15, 0x20000
	s_brev_b32 s14, -2
	v_mov_b32_e32 v226, 1
	s_mov_b32 s50, 0x3f24fd5c
	v_mov_b32_e32 v227, 0x3727c5ac
	v_mov_b32_e32 v228, 0xff800000
	v_mov_b32_e32 v229, 0x4040
	s_branch .LBB0_1346
